# v11 plus: layer 1 w_in bf16 transposition moved from the layer 0 converter workgroups back into the prologue (converter workgroups were on the critical path of the w_in phase)
# speedup vs baseline: 1.0120x; 1.0120x over previous
.LBB0_19:
	s_cmpk_gt_i32 s22, 0x1fff
	v_lshlrev_b32_e32 v67, 3, v69
	s_cbranch_scc1 .LBB0_22
	s_mul_i32 s4, s20, 0x4400
	s_add_i32 s4, s4, 0
	v_lshrrev_b32_e32 v22, 4, v69
	v_and_b32_e32 v2, 60, v68
	v_lshrrev_b32_e32 v23, 3, v69
	v_and_b32_e32 v4, 56, v67
	v_lshl_add_u32 v5, v2, 2, s4
	v_mul_u32_u24_e32 v6, 0x104, v22
	v_mul_u32_u24_e32 v7, 0x104, v4
	v_lshlrev_b32_e32 v8, 2, v23
	s_waitcnt lgkmcnt(0)
	s_add_u32 s16, s6, 0x800000
	v_mov_b32_e32 v3, 0
	v_add3_u32 v24, s4, v7, v8
	v_add_u32_e32 v32, v5, v6
	s_addc_u32 s17, s7, 0
	v_or_b32_e32 v25, 8, v23
	v_or_b32_e32 v26, 16, v23
	v_or_b32_e32 v27, 24, v23
	v_or_b32_e32 v28, 32, v23
	v_or_b32_e32 v29, 40, v23
	v_or_b32_e32 v30, 48, v23
	v_or_b32_e32 v31, 56, v23
	s_mov_b32 s18, 0x2c00000
	s_mov_b32 s19, 0x4200000
	s_movk_i32 s26, 0x800
	v_lshlrev_b32_e32 v2, 2, v2
	v_add_u32_e32 v33, 0x410, v32
	v_add_u32_e32 v34, 0x418, v32
	v_add_u32_e32 v35, 0x820, v32
	v_add_u32_e32 v36, 0x828, v32
	v_add_u32_e32 v37, 0xc30, v32
	v_add_u32_e32 v38, 0xc38, v32
	v_add_u32_e32 v39, 0x1040, v32
	v_add_u32_e32 v40, 0x1048, v32
	v_add_u32_e32 v41, 0x1450, v32
	v_add_u32_e32 v42, 0x1458, v32
	v_add_u32_e32 v43, 0x1860, v32
	v_add_u32_e32 v44, 0x1868, v32
	v_add_u32_e32 v45, 0x1c70, v32
	v_add_u32_e32 v46, 0x1c78, v32
	v_add_u32_e32 v47, 0x2080, v32
	v_add_u32_e32 v48, 0x2088, v32
	v_add_u32_e32 v49, 0x2490, v32
	v_add_u32_e32 v50, 0x2498, v32
	v_add_u32_e32 v51, 0x28a0, v32
	v_add_u32_e32 v52, 0x28a8, v32
	v_add_u32_e32 v53, 0x2cb0, v32
	v_add_u32_e32 v54, 0x2cb8, v32
	v_add_u32_e32 v55, 0x30c0, v32
	v_add_u32_e32 v56, 0x30c8, v32
	v_add_u32_e32 v57, 0x34d0, v32
	v_add_u32_e32 v58, 0x34d8, v32
	v_add_u32_e32 v59, 0x38e0, v32
	v_add_u32_e32 v60, 0x38e8, v32
	v_add_u32_e32 v61, 0x3cf0, v32
	v_add_u32_e32 v62, 0x3cf8, v32
	v_lshlrev_b32_e32 v4, 1, v4
	v_mov_b32_e32 v5, v3
	s_movk_i32 s27, 0x7fff
	s_mov_b32 s28, 0xffff0000
	s_movk_i32 s29, 0x1600
	v_add_u32_e32 v63, 0x400, v24
.LBB0_21:
	s_cmpk_lt_i32 s22, 0x1580
	s_cselect_b32 s99, 0, 0x1a00
	s_add_i32 s99, s99, s22
	s_mul_hi_i32 s4, s99, 0xe070381d
	s_add_i32 s4, s4, s99
	s_lshr_b32 s5, s4, 31
	s_ashr_i32 s4, s4, 13
	s_add_i32 s30, s4, s5
	s_mul_i32 s4, s30, 0xffffdb80
	s_mul_i32 s8, s30, 0xa100000
	s_add_i32 s31, s99, s4
	s_mul_hi_i32 s5, s30, 0xa100000
	s_add_u32 s34, s16, s8
	s_addc_u32 s36, s17, s5
	s_cmpk_lt_i32 s31, 0xb00
	s_cselect_b64 s[4:5], -1, 0
	s_add_i32 s35, s31, 0xf500
	s_and_b64 s[8:9], s[4:5], exec
	s_cselect_b32 s8, 64, 0x48
	s_add_u32 s8, s14, s8
	s_addc_u32 s9, s15, 0
	s_and_b64 s[10:11], s[4:5], exec
	s_load_dwordx2 s[10:11], s[8:9], 0x0
	s_cselect_b32 s8, s18, 0x2a00000
	s_cselect_b32 s38, s31, s35
	s_mul_hi_i32 s31, s8, s30
	s_mul_i32 s8, s8, s30
	s_cselect_b32 s37, 0x2c00000, s19
	s_cselect_b32 s9, s26, 0x1500
	s_waitcnt lgkmcnt(0)
	s_add_u32 s35, s10, s8
	s_addc_u32 s31, s11, s31
	s_lshr_b32 s8, s9, 6
	s_sext_i32_i16 s10, s8
	v_cvt_f32_i32_e32 v7, s10
	s_sext_i32_i16 s30, s38
	v_cvt_f32_i32_e32 v6, s30
	s_xor_b32 s10, s30, s10
	v_rcp_iflag_f32_e32 v8, v7
	s_ashr_i32 s10, s10, 30
	s_or_b32 s30, s10, 1
	v_mul_f32_e32 v8, v6, v8
	v_trunc_f32_e32 v8, v8
	v_fma_f32 v6, -v8, v7, v6
	v_cvt_i32_f32_e32 v8, v8
	v_cmp_ge_f32_e64 s[10:11], |v6|, |v7|
	s_and_b64 s[10:11], s[10:11], exec
	s_cselect_b32 s10, s30, 0
	v_readfirstlane_b32 s11, v8
	s_add_i32 s10, s11, s10
	s_sext_i32_i16 s11, s10
	s_mul_i32 s10, s10, s8
	s_sub_i32 s8, s38, s10
	s_sext_i32_i16 s10, s8
	s_add_u32 s34, s34, s37
	s_addc_u32 s30, s36, 0
	s_lshl_b32 s10, s10, 6
	s_lshl_b32 s8, s11, 6
	s_ashr_i32 s11, s10, 31
	v_or_b32_e32 v136, s10, v23
	v_or_b32_e32 v137, s10, v25
	v_or_b32_e32 v138, s10, v26
	v_or_b32_e32 v139, s10, v27
	v_or_b32_e32 v140, s10, v28
	v_or_b32_e32 v141, s10, v29
	v_or_b32_e32 v142, s10, v30
	v_or_b32_e32 v143, s10, v31
	s_lshl_b64 s[10:11], s[10:11], 2
	v_or_b32_e32 v8, s8, v22
	s_add_u32 s10, s35, s10
	v_or_b32_e32 v10, 4, v8
	v_or_b32_e32 v12, 8, v8
	v_or_b32_e32 v14, 12, v8
	v_or_b32_e32 v16, 16, v8
	v_or_b32_e32 v18, 20, v8
	v_or_b32_e32 v20, 24, v8
	v_or_b32_e32 v64, 28, v8
	v_or_b32_e32 v70, 32, v8
	v_or_b32_e32 v72, 36, v8
	v_or_b32_e32 v74, 40, v8
	v_or_b32_e32 v76, 44, v8
	v_or_b32_e32 v78, 48, v8
	v_or_b32_e32 v80, 52, v8
	v_or_b32_e32 v82, 56, v8
	v_or_b32_e32 v84, 60, v8
	s_addc_u32 s11, s31, s11
	v_mul_hi_i32_i24_e32 v7, s9, v8
	v_mul_i32_i24_e32 v6, s9, v8
	v_mul_hi_i32_i24_e32 v9, s9, v10
	v_mul_i32_i24_e32 v8, s9, v10
	v_mul_hi_i32_i24_e32 v11, s9, v12
	v_mul_i32_i24_e32 v10, s9, v12
	v_mul_hi_i32_i24_e32 v13, s9, v14
	v_mul_i32_i24_e32 v12, s9, v14
	v_mul_hi_i32_i24_e32 v15, s9, v16
	v_mul_i32_i24_e32 v14, s9, v16
	v_mul_hi_i32_i24_e32 v17, s9, v18
	v_mul_i32_i24_e32 v16, s9, v18
	v_mul_hi_i32_i24_e32 v19, s9, v20
	v_mul_i32_i24_e32 v18, s9, v20
	v_mul_hi_i32_i24_e32 v21, s9, v64
	v_mul_i32_i24_e32 v20, s9, v64
	v_mul_hi_i32_i24_e32 v65, s9, v70
	v_mul_i32_i24_e32 v64, s9, v70
	v_mul_hi_i32_i24_e32 v71, s9, v72
	v_mul_i32_i24_e32 v70, s9, v72
	v_mul_hi_i32_i24_e32 v73, s9, v74
	v_mul_i32_i24_e32 v72, s9, v74
	v_mul_hi_i32_i24_e32 v75, s9, v76
	v_mul_i32_i24_e32 v74, s9, v76
	v_mul_hi_i32_i24_e32 v77, s9, v78
	v_mul_i32_i24_e32 v76, s9, v78
	v_mul_hi_i32_i24_e32 v79, s9, v80
	v_mul_i32_i24_e32 v78, s9, v80
	v_mul_hi_i32_i24_e32 v81, s9, v82
	v_mul_i32_i24_e32 v80, s9, v82
	v_mul_hi_i32_i24_e32 v83, s9, v84
	v_mul_i32_i24_e32 v82, s9, v84
	v_lshl_add_u64 v[84:85], s[10:11], 0, v[2:3]
	v_lshl_add_u64 v[6:7], v[6:7], 2, v[84:85]
	v_lshl_add_u64 v[122:123], v[70:71], 2, v[84:85]
	v_lshl_add_u64 v[124:125], v[72:73], 2, v[84:85]
	v_lshl_add_u64 v[126:127], v[74:75], 2, v[84:85]
	v_lshl_add_u64 v[128:129], v[76:77], 2, v[84:85]
	v_lshl_add_u64 v[130:131], v[78:79], 2, v[84:85]
	v_lshl_add_u64 v[132:133], v[80:81], 2, v[84:85]
	v_lshl_add_u64 v[8:9], v[8:9], 2, v[84:85]
	v_lshl_add_u64 v[10:11], v[10:11], 2, v[84:85]
	v_lshl_add_u64 v[12:13], v[12:13], 2, v[84:85]
	v_lshl_add_u64 v[14:15], v[14:15], 2, v[84:85]
	v_lshl_add_u64 v[16:17], v[16:17], 2, v[84:85]
	v_lshl_add_u64 v[18:19], v[18:19], 2, v[84:85]
	v_lshl_add_u64 v[20:21], v[20:21], 2, v[84:85]
	v_lshl_add_u64 v[64:65], v[64:65], 2, v[84:85]
	v_lshl_add_u64 v[134:135], v[82:83], 2, v[84:85]
	global_load_dwordx4 v[70:73], v[6:7], off nt
	global_load_dwordx4 v[74:77], v[8:9], off nt
	global_load_dwordx4 v[78:81], v[10:11], off nt
	global_load_dwordx4 v[82:85], v[12:13], off nt
	global_load_dwordx4 v[86:89], v[14:15], off nt
	global_load_dwordx4 v[90:93], v[16:17], off nt
	global_load_dwordx4 v[94:97], v[18:19], off nt
	global_load_dwordx4 v[98:101], v[20:21], off nt
	global_load_dwordx4 v[102:105], v[64:65], off nt
	global_load_dwordx4 v[106:109], v[122:123], off nt
	global_load_dwordx4 v[110:113], v[124:125], off nt
	global_load_dwordx4 v[114:117], v[126:127], off nt
	global_load_dwordx4 v[118:121], v[128:129], off nt
	s_nop 0
	global_load_dwordx4 v[122:125], v[130:131], off nt
	global_load_dwordx4 v[126:129], v[132:133], off nt
	s_nop 0
	global_load_dwordx4 v[130:133], v[134:135], off nt
	s_ashr_i32 s9, s8, 31
	s_lshl_b64 s[8:9], s[8:9], 1
	s_add_u32 s8, s34, s8
	s_addc_u32 s9, s30, s9
	s_and_b64 s[4:5], s[4:5], exec
	s_waitcnt vmcnt(15)
	ds_write2_b32 v32, v70, v71 offset1:1
	ds_write2_b32 v32, v72, v73 offset0:2 offset1:3
	s_waitcnt vmcnt(14)
	ds_write2_b32 v33, v74, v75 offset1:1
	ds_write2_b32 v34, v76, v77 offset1:1
	s_waitcnt vmcnt(13)
	ds_write2_b32 v35, v78, v79 offset1:1
	ds_write2_b32 v36, v80, v81 offset1:1
	s_waitcnt vmcnt(12)
	ds_write2_b32 v37, v82, v83 offset1:1
	ds_write2_b32 v38, v84, v85 offset1:1
	s_waitcnt vmcnt(11)
	ds_write2_b32 v39, v86, v87 offset1:1
	ds_write2_b32 v40, v88, v89 offset1:1
	s_waitcnt vmcnt(10)
	ds_write2_b32 v41, v90, v91 offset1:1
	ds_write2_b32 v42, v92, v93 offset1:1
	s_waitcnt vmcnt(9)
	ds_write2_b32 v43, v94, v95 offset1:1
	ds_write2_b32 v44, v96, v97 offset1:1
	s_waitcnt vmcnt(8)
	ds_write2_b32 v45, v98, v99 offset1:1
	ds_write2_b32 v46, v100, v101 offset1:1
	s_waitcnt vmcnt(7)
	ds_write2_b32 v47, v102, v103 offset1:1
	ds_write2_b32 v48, v104, v105 offset1:1
	s_waitcnt vmcnt(6)
	ds_write2_b32 v49, v106, v107 offset1:1
	ds_write2_b32 v50, v108, v109 offset1:1
	s_waitcnt vmcnt(5)
	ds_write2_b32 v51, v110, v111 offset1:1
	ds_write2_b32 v52, v112, v113 offset1:1
	s_waitcnt vmcnt(4)
	ds_write2_b32 v53, v114, v115 offset1:1
	ds_write2_b32 v54, v116, v117 offset1:1
	s_waitcnt vmcnt(3)
	ds_write2_b32 v55, v118, v119 offset1:1
	ds_write2_b32 v56, v120, v121 offset1:1
	s_waitcnt vmcnt(2)
	ds_write2_b32 v57, v122, v123 offset1:1
	ds_write2_b32 v58, v124, v125 offset1:1
	s_waitcnt vmcnt(1)
	ds_write2_b32 v59, v126, v127 offset1:1
	ds_write2_b32 v60, v128, v129 offset1:1
	s_waitcnt vmcnt(0)
	ds_write2_b32 v61, v130, v131 offset1:1
	ds_write2_b32 v62, v132, v133 offset1:1
	s_cselect_b32 s4, s29, 0x800
	s_waitcnt lgkmcnt(0)
	v_lshl_add_u64 v[20:21], s[8:9], 0, v[4:5]
	v_mul_hi_i32_i24_e32 v7, s4, v136
	v_mul_i32_i24_e32 v6, s4, v136
	v_mul_hi_i32_i24_e32 v9, s4, v137
	v_mul_i32_i24_e32 v8, s4, v137
	v_mul_hi_i32_i24_e32 v11, s4, v138
	v_mul_i32_i24_e32 v10, s4, v138
	v_mul_hi_i32_i24_e32 v13, s4, v139
	v_mul_i32_i24_e32 v12, s4, v139
	v_mul_hi_i32_i24_e32 v15, s4, v140
	v_mul_i32_i24_e32 v14, s4, v140
	v_mul_hi_i32_i24_e32 v17, s4, v141
	v_mul_i32_i24_e32 v16, s4, v141
	v_mul_hi_i32_i24_e32 v19, s4, v142
	v_mul_i32_i24_e32 v18, s4, v142
	v_mul_hi_i32_i24_e32 v65, s4, v143
	v_mul_i32_i24_e32 v64, s4, v143
	v_lshl_add_u64 v[6:7], v[6:7], 1, v[20:21]
	v_lshl_add_u64 v[8:9], v[8:9], 1, v[20:21]
	v_lshl_add_u64 v[10:11], v[10:11], 1, v[20:21]
	v_lshl_add_u64 v[12:13], v[12:13], 1, v[20:21]
	v_lshl_add_u64 v[14:15], v[14:15], 1, v[20:21]
	v_lshl_add_u64 v[16:17], v[16:17], 1, v[20:21]
	v_lshl_add_u64 v[18:19], v[18:19], 1, v[20:21]
	v_lshl_add_u64 v[20:21], v[64:65], 1, v[20:21]
	ds_read2_b32 v[64:65], v24 offset0:65 offset1:73
	ds_read2_b32 v[70:71], v24 offset1:8
	ds_read2_b32 v[72:73], v24 offset0:130 offset1:138
	ds_read2_b32 v[74:75], v24 offset0:195 offset1:203
	ds_read2_b32 v[76:77], v63 offset0:4 offset1:12
	ds_read2_b32 v[78:79], v63 offset0:69 offset1:77
	ds_read2_b32 v[80:81], v63 offset0:134 offset1:142
	ds_read2_b32 v[82:83], v63 offset0:199 offset1:207
	ds_read2_b32 v[84:85], v24 offset0:16 offset1:24
	ds_read2_b32 v[86:87], v24 offset0:81 offset1:89
	ds_read2_b32 v[88:89], v24 offset0:146 offset1:154
	ds_read2_b32 v[90:91], v24 offset0:211 offset1:219
	ds_read2_b32 v[92:93], v63 offset0:20 offset1:28
	ds_read2_b32 v[94:95], v63 offset0:85 offset1:93
	ds_read2_b32 v[96:97], v63 offset0:150 offset1:158
	ds_read2_b32 v[98:99], v63 offset0:215 offset1:223
	ds_read2_b32 v[100:101], v24 offset0:32 offset1:40
	ds_read2_b32 v[102:103], v24 offset0:97 offset1:105
	ds_read2_b32 v[104:105], v24 offset0:162 offset1:170
	ds_read2_b32 v[106:107], v24 offset0:227 offset1:235
	ds_read2_b32 v[108:109], v63 offset0:36 offset1:44
	ds_read2_b32 v[110:111], v63 offset0:101 offset1:109
	ds_read2_b32 v[112:113], v63 offset0:166 offset1:174
	ds_read2_b32 v[114:115], v63 offset0:231 offset1:239
	ds_read2_b32 v[116:117], v24 offset0:48 offset1:56
	ds_read2_b32 v[118:119], v24 offset0:113 offset1:121
	ds_read2_b32 v[120:121], v24 offset0:178 offset1:186
	ds_read2_b32 v[122:123], v24 offset0:243 offset1:251
	ds_read2_b32 v[124:125], v63 offset0:52 offset1:60
	ds_read2_b32 v[126:127], v63 offset0:117 offset1:125
	ds_read2_b32 v[128:129], v63 offset0:182 offset1:190
	ds_read2_b32 v[130:131], v63 offset0:247 offset1:255
	s_waitcnt lgkmcnt(14)
	v_bfe_u32 v132, v70, 16, 1
	v_bfe_u32 v134, v72, 16, 1
	v_bfe_u32 v136, v76, 16, 1
	v_bfe_u32 v138, v80, 16, 1
	v_bfe_u32 v133, v64, 16, 1
	v_bfe_u32 v135, v74, 16, 1
	v_bfe_u32 v137, v78, 16, 1
	v_bfe_u32 v139, v82, 16, 1
	v_bfe_u32 v140, v71, 16, 1
	v_bfe_u32 v142, v73, 16, 1
	v_bfe_u32 v144, v77, 16, 1
	v_bfe_u32 v146, v81, 16, 1
	v_bfe_u32 v148, v84, 16, 1
	v_bfe_u32 v150, v88, 16, 1
	v_bfe_u32 v152, v92, 16, 1
	v_bfe_u32 v154, v96, 16, 1
	v_bfe_u32 v156, v85, 16, 1
	v_bfe_u32 v158, v89, 16, 1
	v_bfe_u32 v160, v93, 16, 1
	v_bfe_u32 v162, v97, 16, 1
	v_bfe_u32 v164, v100, 16, 1
	s_waitcnt lgkmcnt(13)
	v_bfe_u32 v166, v104, 16, 1
	s_waitcnt lgkmcnt(11)
	v_bfe_u32 v168, v108, 16, 1
	s_waitcnt lgkmcnt(9)
	v_bfe_u32 v170, v112, 16, 1
	v_bfe_u32 v172, v101, 16, 1
	v_bfe_u32 v174, v105, 16, 1
	v_bfe_u32 v176, v109, 16, 1
	v_bfe_u32 v178, v113, 16, 1
	s_waitcnt lgkmcnt(7)
	v_bfe_u32 v180, v116, 16, 1
	s_waitcnt lgkmcnt(5)
	v_bfe_u32 v182, v120, 16, 1
	s_waitcnt lgkmcnt(3)
	v_bfe_u32 v184, v124, 16, 1
	s_waitcnt lgkmcnt(1)
	v_bfe_u32 v186, v128, 16, 1
	v_bfe_u32 v188, v117, 16, 1
	v_bfe_u32 v190, v121, 16, 1
	v_bfe_u32 v192, v125, 16, 1
	v_bfe_u32 v194, v129, 16, 1
	v_add3_u32 v70, v70, v132, s27
	v_add3_u32 v72, v72, v134, s27
	v_add3_u32 v76, v76, v136, s27
	v_add3_u32 v80, v80, v138, s27
	v_bfe_u32 v141, v65, 16, 1
	v_bfe_u32 v143, v75, 16, 1
	v_bfe_u32 v145, v79, 16, 1
	v_bfe_u32 v147, v83, 16, 1
	v_bfe_u32 v149, v86, 16, 1
	v_bfe_u32 v151, v90, 16, 1
	v_bfe_u32 v153, v94, 16, 1
	v_bfe_u32 v155, v98, 16, 1
	v_bfe_u32 v157, v87, 16, 1
	v_bfe_u32 v159, v91, 16, 1
	v_bfe_u32 v161, v95, 16, 1
	v_bfe_u32 v163, v99, 16, 1
	v_bfe_u32 v165, v102, 16, 1
	v_bfe_u32 v167, v106, 16, 1
	v_bfe_u32 v169, v110, 16, 1
	v_bfe_u32 v171, v114, 16, 1
	v_bfe_u32 v173, v103, 16, 1
	v_bfe_u32 v175, v107, 16, 1
	v_bfe_u32 v177, v111, 16, 1
	v_bfe_u32 v179, v115, 16, 1
	v_bfe_u32 v181, v118, 16, 1
	v_bfe_u32 v183, v122, 16, 1
	v_bfe_u32 v185, v126, 16, 1
	s_waitcnt lgkmcnt(0)
	v_bfe_u32 v187, v130, 16, 1
	v_bfe_u32 v189, v119, 16, 1
	v_bfe_u32 v191, v123, 16, 1
	v_bfe_u32 v193, v127, 16, 1
	v_bfe_u32 v195, v131, 16, 1
	v_add3_u32 v64, v64, v133, s27
	v_add3_u32 v74, v74, v135, s27
	v_add3_u32 v78, v78, v137, s27
	v_add3_u32 v82, v82, v139, s27
	v_add3_u32 v71, v71, v140, s27
	v_add3_u32 v73, v73, v142, s27
	v_add3_u32 v77, v77, v144, s27
	v_add3_u32 v81, v81, v146, s27
	v_add3_u32 v84, v84, v148, s27
	v_add3_u32 v88, v88, v150, s27
	v_add3_u32 v92, v92, v152, s27
	v_add3_u32 v96, v96, v154, s27
	v_add3_u32 v85, v85, v156, s27
	v_add3_u32 v89, v89, v158, s27
	v_add3_u32 v93, v93, v160, s27
	v_add3_u32 v97, v97, v162, s27
	v_add3_u32 v100, v100, v164, s27
	v_add3_u32 v104, v104, v166, s27
	v_add3_u32 v108, v108, v168, s27
	v_add3_u32 v112, v112, v170, s27
	v_add3_u32 v101, v101, v172, s27
	v_add3_u32 v105, v105, v174, s27
	v_add3_u32 v109, v109, v176, s27
	v_add3_u32 v113, v113, v178, s27
	v_add3_u32 v116, v116, v180, s27
	v_add3_u32 v120, v120, v182, s27
	v_add3_u32 v124, v124, v184, s27
	v_add3_u32 v128, v128, v186, s27
	v_add3_u32 v117, v117, v188, s27
	v_add3_u32 v121, v121, v190, s27
	v_add3_u32 v125, v125, v192, s27
	v_add3_u32 v129, v129, v194, s27
	v_lshrrev_b32_e32 v70, 16, v70
	v_lshrrev_b32_e32 v72, 16, v72
	v_lshrrev_b32_e32 v76, 16, v76
	v_lshrrev_b32_e32 v80, 16, v80
	v_add3_u32 v65, v65, v141, s27
	v_add3_u32 v75, v75, v143, s27
	v_add3_u32 v79, v79, v145, s27
	v_add3_u32 v83, v83, v147, s27
	v_add3_u32 v86, v86, v149, s27
	v_add3_u32 v90, v90, v151, s27
	v_add3_u32 v94, v94, v153, s27
	v_add3_u32 v98, v98, v155, s27
	v_add3_u32 v87, v87, v157, s27
	v_add3_u32 v91, v91, v159, s27
	v_add3_u32 v95, v95, v161, s27
	v_add3_u32 v99, v99, v163, s27
	v_add3_u32 v102, v102, v165, s27
	v_add3_u32 v106, v106, v167, s27
	v_add3_u32 v110, v110, v169, s27
	v_add3_u32 v114, v114, v171, s27
	v_add3_u32 v103, v103, v173, s27
	v_add3_u32 v107, v107, v175, s27
	v_add3_u32 v111, v111, v177, s27
	v_add3_u32 v115, v115, v179, s27
	v_add3_u32 v118, v118, v181, s27
	v_add3_u32 v122, v122, v183, s27
	v_add3_u32 v126, v126, v185, s27
	v_add3_u32 v130, v130, v187, s27
	v_add3_u32 v119, v119, v189, s27
	v_add3_u32 v123, v123, v191, s27
	v_add3_u32 v127, v127, v193, s27
	v_add3_u32 v131, v131, v195, s27
	v_lshrrev_b32_e32 v132, 16, v71
	v_lshrrev_b32_e32 v133, 16, v73
	v_lshrrev_b32_e32 v77, 16, v77
	v_lshrrev_b32_e32 v81, 16, v81
	v_lshrrev_b32_e32 v84, 16, v84
	v_lshrrev_b32_e32 v88, 16, v88
	v_lshrrev_b32_e32 v92, 16, v92
	v_lshrrev_b32_e32 v96, 16, v96
	v_lshrrev_b32_e32 v85, 16, v85
	v_lshrrev_b32_e32 v89, 16, v89
	v_lshrrev_b32_e32 v93, 16, v93
	v_lshrrev_b32_e32 v97, 16, v97
	v_lshrrev_b32_e32 v100, 16, v100
	v_lshrrev_b32_e32 v104, 16, v104
	v_lshrrev_b32_e32 v108, 16, v108
	v_lshrrev_b32_e32 v112, 16, v112
	v_lshrrev_b32_e32 v101, 16, v101
	v_lshrrev_b32_e32 v105, 16, v105
	v_lshrrev_b32_e32 v109, 16, v109
	v_lshrrev_b32_e32 v113, 16, v113
	v_lshrrev_b32_e32 v116, 16, v116
	v_lshrrev_b32_e32 v120, 16, v120
	v_lshrrev_b32_e32 v124, 16, v124
	v_lshrrev_b32_e32 v128, 16, v128
	v_lshrrev_b32_e32 v117, 16, v117
	v_lshrrev_b32_e32 v121, 16, v121
	v_lshrrev_b32_e32 v125, 16, v125
	v_lshrrev_b32_e32 v129, 16, v129
	v_and_or_b32 v70, v64, s28, v70
	v_and_or_b32 v71, v74, s28, v72
	v_and_or_b32 v72, v78, s28, v76
	v_and_or_b32 v73, v82, s28, v80
	v_and_or_b32 v74, v65, s28, v132
	v_and_or_b32 v75, v75, s28, v133
	v_and_or_b32 v76, v79, s28, v77
	v_and_or_b32 v77, v83, s28, v81
	v_and_or_b32 v78, v86, s28, v84
	v_and_or_b32 v79, v90, s28, v88
	v_and_or_b32 v80, v94, s28, v92
	v_and_or_b32 v81, v98, s28, v96
	v_and_or_b32 v82, v87, s28, v85
	v_and_or_b32 v83, v91, s28, v89
	v_and_or_b32 v84, v95, s28, v93
	v_and_or_b32 v85, v99, s28, v97
	v_and_or_b32 v86, v102, s28, v100
	v_and_or_b32 v87, v106, s28, v104
	v_and_or_b32 v88, v110, s28, v108
	v_and_or_b32 v89, v114, s28, v112
	v_and_or_b32 v90, v103, s28, v101
	v_and_or_b32 v91, v107, s28, v105
	v_and_or_b32 v92, v111, s28, v109
	v_and_or_b32 v93, v115, s28, v113
	v_and_or_b32 v94, v118, s28, v116
	v_and_or_b32 v95, v122, s28, v120
	v_and_or_b32 v96, v126, s28, v124
	v_and_or_b32 v97, v130, s28, v128
	v_and_or_b32 v98, v119, s28, v117
	v_and_or_b32 v99, v123, s28, v121
	v_and_or_b32 v100, v127, s28, v125
	v_and_or_b32 v101, v131, s28, v129
	global_store_dwordx4 v[6:7], v[70:73], off
	global_store_dwordx4 v[8:9], v[74:77], off
	global_store_dwordx4 v[10:11], v[78:81], off
	global_store_dwordx4 v[12:13], v[82:85], off
	global_store_dwordx4 v[14:15], v[86:89], off
	global_store_dwordx4 v[16:17], v[90:93], off
	global_store_dwordx4 v[18:19], v[94:97], off
	global_store_dwordx4 v[20:21], v[98:101], off
	s_waitcnt lgkmcnt(0)
	s_add_i32 s22, s22, s23
	s_cmpk_gt_i32 s22, 0x1fff
	s_cbranch_scc0 .LBB0_21

.LBB0_700:
	s_andn2_b64 vcc, exec, s[4:5]
	s_cbranch_vccnz .LBB0_909
	s_mov_b64 s[18:19], s[0:1]
	s_load_dwordx2 s[14:15], s[18:19], 0x80
	v_mov_b32_e32 v130, v0
	s_mov_b32 s4, s33
	s_waitcnt lgkmcnt(0)
	s_mov_b32 s43, s85
	s_mov_b32 s55, s2
	s_sub_i32 s39, s43, 32
	v_readfirstlane_b32 s6, v130
	s_cmp_ge_i32 s55, s39
	s_mov_b64 s[4:5], -1
	s_cbranch_scc0 .LBB0_806
	v_readlane_b32 s8, v255, 29
	s_ashr_i32 s34, s6, 6
	v_readlane_b32 s9, v255, 30
	s_and_b64 s[4:5], s[8:9], exec
	s_cselect_b32 s4, 0x100, 0
	v_readlane_b32 s5, v255, 21
	s_add_u32 s16, s5, s4
	v_readlane_b32 s4, v255, 22
	v_and_b32_e32 v1, 63, v130
	s_addc_u32 s17, s4, 0
	s_andn2_b64 vcc, exec, s[8:9]
	s_movk_i32 s47, 0x1a00
	s_cbranch_vccnz .LBB0_723
	s_andn2_b32 s6, s6, 63
	v_or_b32_e32 v66, s6, v1
	v_cmp_eq_u32_e64 s[4:5], 0, v66
	s_barrier
	s_and_saveexec_b64 s[6:7], s[4:5]
	s_cbranch_execz .LBB0_707
	s_mov_b64 s[10:11], exec
	s_waitcnt vmcnt(0)
	v_mbcnt_lo_u32_b32 v2, s10, 0
	v_mbcnt_hi_u32_b32 v2, s11, v2
	v_cmp_eq_u32_e32 vcc, 0, v2
	s_and_saveexec_b64 s[8:9], vcc
	s_cbranch_execz .LBB0_706
	s_bcnt1_i32_b64 s10, s[10:11]
	v_mov_b32_e32 v3, s10
	global_atomic_add v3, v223, v3, s[16:17] offset:64 sc0
